# grid barrier cross-XCD level one-way: each XCD leader adds an arrival to every XCD word (non-returning), all WGs wait on their XCD word; no returning global atomic, no relay
# baseline (speedup 1.0000x reference)
; __device__ __forceinline__ unsigned xb_ld(unsigned* p)              { return __hip_atomic_load(p, __ATOMIC_RELAXED, __HIP_MEMORY_SCOPE_AGENT); }
; __device__ __forceinline__ unsigned xb_add(unsigned* p, unsigned v) { return __hip_atomic_fetch_add(p, v, __ATOMIC_RELAXED, __HIP_MEMORY_SCOPE_AGENT); }
; #define XB_SPIN(cond, bar) do { unsigned _sp = 0; while (cond) { __builtin_amdgcn_s_sleep(1); \
;     if ((++_sp & 255u) == 0u) { if (xb_ld(&(bar)[XB_TMO])) break; if (_sp > XB_SPIN_CAP) { atomicAdd(&(bar)[XB_TMO], 1u); break; } } } } while (0)
; __device__ __forceinline__ void xcd_barrier(unsigned* bar, volatile LAS unsigned* st) {
;     ...
;         const unsigned old = xb_add(&bar[XB_XSUB(x)], 1u);
;         const unsigned gen = old / nloc;
;         if (old + 1u == (gen + 1u) * nloc) {
;             __builtin_amdgcn_fence(__ATOMIC_RELEASE, "agent");
;             asm volatile("s_waitcnt vmcnt(0)" ::: "memory");
;             const unsigned og = xb_add(&bar[XB_TOP], 1u);
;             const unsigned tg = og / nx;
;             if (og + 1u == (tg + 1u) * nx) xb_add(&bar[XB_TOPGEN], 1u);
;             else XB_SPIN(xb_ld(&bar[XB_TOPGEN]) == tg, bar);
;             __builtin_amdgcn_fence(__ATOMIC_ACQUIRE, "agent");
;             xb_add(&bar[XB_XGEN(x)], 1u);
;             asm volatile("s_waitcnt vmcnt(0)" ::: "memory");
;         } else {
;             XB_SPIN(xb_ld(&bar[XB_XGEN(x)]) == gen, bar);
.LBB0_29:
	s_or_b64 exec, exec, s[10:11]
	v_cvt_f32_u32_e32 v5, v3
	s_waitcnt vmcnt(0)
	v_readfirstlane_b32 s4, v4
	v_sub_u32_e32 v4, 0, v3
	v_rcp_iflag_f32_e32 v5, v5
	v_add_u32_e32 v6, s4, v2
	v_mul_f32_e32 v5, 0x4f7ffffe, v5
	v_cvt_u32_f32_e32 v5, v5
	v_mul_lo_u32 v2, v4, v5
	v_mul_hi_u32 v2, v5, v2
	v_add_u32_e32 v2, v5, v2
	v_mul_hi_u32 v2, v6, v2
	v_mul_lo_u32 v4, v2, v3
	v_sub_u32_e32 v4, v6, v4
	v_add_u32_e32 v5, 1, v2
	v_sub_u32_e32 v7, v4, v3
	v_cmp_ge_u32_e32 vcc, v4, v3
	s_nop 1
	v_cndmask_b32_e32 v2, v2, v5, vcc
	v_cndmask_b32_e32 v4, v4, v7, vcc
	v_add_u32_e32 v5, 1, v2
	v_cmp_ge_u32_e32 vcc, v4, v3
	v_add_u32_e32 v4, 1, v6
	s_nop 0
	v_cndmask_b32_e32 v2, v2, v5, vcc
	v_mul_lo_u32 v5, v3, v2
	v_add_u32_e32 v3, v5, v3
	v_cmp_ne_u32_e32 vcc, v4, v3
	s_and_saveexec_b64 s[8:9], vcc
	s_xor_b64 s[8:9], exec, s[8:9]
	s_cbranch_execz .LBB0_43
	s_waitcnt lgkmcnt(0)
	v_mad_u32_u24 v3, v2, v0, v0
	s_add_u32 s14, s6, 0x2400
	s_addc_u32 s15, s7, 0
	s_nop 1
	global_load_dword v0, v1, s[14:15] sc1
	s_waitcnt vmcnt(0)
	v_cmp_gt_u32_e32 vcc, v3, v0
	s_and_saveexec_b64 s[10:11], vcc
	s_cbranch_execz .LBB0_42
	s_add_u32 s12, s2, 0x3c00200
	s_addc_u32 s13, s3, 0
	s_mov_b32 s4, 1
	s_mov_b64 s[16:17], 0
	s_branch .LBB0_33

; __device__ __forceinline__ unsigned xb_ld(unsigned* p)              { return __hip_atomic_load(p, __ATOMIC_RELAXED, __HIP_MEMORY_SCOPE_AGENT); }
; #define XB_SPIN(cond, bar) do { unsigned _sp = 0; while (cond) { __builtin_amdgcn_s_sleep(1); \
;     if ((++_sp & 255u) == 0u) { if (xb_ld(&(bar)[XB_TMO])) break; if (_sp > XB_SPIN_CAP) { atomicAdd(&(bar)[XB_TMO], 1u); break; } } } } while (0)
; __device__ __forceinline__ void xcd_barrier(unsigned* bar, volatile LAS unsigned* st) {
;     ...
;             XB_SPIN(xb_ld(&bar[XB_XGEN(x)]) == gen, bar);
.LBB0_37:
	global_load_dword v0, v1, s[14:15] sc1
	s_add_i32 s4, s4, 1
	s_mov_b64 s[22:23], -1
	s_waitcnt vmcnt(0)
	v_cmp_le_u32_e32 vcc, v3, v0
	s_orn2_b64 s[20:21], vcc, exec
	s_branch .LBB0_32

; __device__ __forceinline__ unsigned xb_ld(unsigned* p)              { return __hip_atomic_load(p, __ATOMIC_RELAXED, __HIP_MEMORY_SCOPE_AGENT); }
; __device__ __forceinline__ unsigned xb_add(unsigned* p, unsigned v) { return __hip_atomic_fetch_add(p, v, __ATOMIC_RELAXED, __HIP_MEMORY_SCOPE_AGENT); }
; #define XB_SPIN(cond, bar) do { unsigned _sp = 0; while (cond) { __builtin_amdgcn_s_sleep(1); \
;     if ((++_sp & 255u) == 0u) { if (xb_ld(&(bar)[XB_TMO])) break; if (_sp > XB_SPIN_CAP) { atomicAdd(&(bar)[XB_TMO], 1u); break; } } } } while (0)
; __device__ __forceinline__ void xcd_barrier(unsigned* bar, volatile LAS unsigned* st) {
;     ...
;         if (old + 1u == (gen + 1u) * nloc) {
;             __builtin_amdgcn_fence(__ATOMIC_RELEASE, "agent");
;             asm volatile("s_waitcnt vmcnt(0)" ::: "memory");
;             const unsigned og = xb_add(&bar[XB_TOP], 1u);
;             const unsigned tg = og / nx;
;             if (og + 1u == (tg + 1u) * nx) xb_add(&bar[XB_TOPGEN], 1u);
;             else XB_SPIN(xb_ld(&bar[XB_TOPGEN]) == tg, bar);
;             __builtin_amdgcn_fence(__ATOMIC_ACQUIRE, "agent");
;             xb_add(&bar[XB_XGEN(x)], 1u);
;             asm volatile("s_waitcnt vmcnt(0)" ::: "memory");
;         } else {
;             XB_SPIN(xb_ld(&bar[XB_XGEN(x)]) == gen, bar);
;             __builtin_amdgcn_fence(__ATOMIC_ACQUIRE, "agent");
;             asm volatile("s_waitcnt vmcnt(0)" ::: "memory");
;         }
.LBB0_43:
	s_andn2_saveexec_b64 s[8:9], s[8:9]
	s_cbranch_execz .LBB0_63
	buffer_wbl2 sc1
	s_waitcnt lgkmcnt(0)
	s_waitcnt vmcnt(0)
	v_mad_u32_u24 v3, v2, v0, v0
	v_mov_b32_e32 v8, 1
	v_mov_b32_e32 v7, 0x3c02400
	global_atomic_add v7, v8, s[2:3]
	v_mov_b32_e32 v7, 0x3c02500
	global_atomic_add v7, v8, s[2:3]
	v_mov_b32_e32 v7, 0x3c02600
	global_atomic_add v7, v8, s[2:3]
	v_mov_b32_e32 v7, 0x3c02700
	global_atomic_add v7, v8, s[2:3]
	v_mov_b32_e32 v7, 0x3c02800
	global_atomic_add v7, v8, s[2:3]
	v_mov_b32_e32 v7, 0x3c02900
	global_atomic_add v7, v8, s[2:3]
	v_mov_b32_e32 v7, 0x3c02a00
	global_atomic_add v7, v8, s[2:3]
	v_mov_b32_e32 v7, 0x3c02b00
	global_atomic_add v7, v8, s[2:3]
	v_mov_b32_e32 v7, 0x3c02c00
	global_atomic_add v7, v8, s[2:3]
	v_mov_b32_e32 v7, 0x3c02d00
	global_atomic_add v7, v8, s[2:3]
	v_mov_b32_e32 v7, 0x3c02e00
	global_atomic_add v7, v8, s[2:3]
	v_mov_b32_e32 v7, 0x3c02f00
	global_atomic_add v7, v8, s[2:3]
	v_mov_b32_e32 v7, 0x3c03000
	global_atomic_add v7, v8, s[2:3]
	v_mov_b32_e32 v7, 0x3c03100
	global_atomic_add v7, v8, s[2:3]
	v_mov_b32_e32 v7, 0x3c03200
	global_atomic_add v7, v8, s[2:3]
	v_mov_b32_e32 v7, 0x3c03300
	global_atomic_add v7, v8, s[2:3]
	s_add_u32 s14, s6, 0x2400
	s_addc_u32 s15, s7, 0
	s_mov_b32 s4, 0
.Lxb_lspin:
	global_load_dword v4, v1, s[14:15] sc1
	s_add_i32 s4, s4, 1
	s_waitcnt vmcnt(0)
	v_cmp_le_u32_e32 vcc, v3, v4
	s_cbranch_vccnz .Lxb_ldone
	s_cmp_lt_u32 s4, 0x20000
	s_cbranch_scc0 .Lxb_ldone
	s_sleep 1
	s_branch .Lxb_lspin
.Lxb_ldone:
	buffer_inv sc1
	s_waitcnt vmcnt(0)
